# PB f32->bf16 conversion loop: 4 loads per trip issued together with saved exec masks, one wait, then 4 cvt+stores
# speedup vs baseline: 1.0316x; 1.0063x over previous
; DI unsigned pk2(float a, float b) { f32x2 v = {a, b}; bf16x2_t r = __builtin_convertvector(v, bf16x2_t); return __builtin_bit_cast(unsigned, r); }
; __global__ void __launch_bounds__(NTHR, 2) hybrid_fwd(Args a_unused) {
;     ...
;             if (c == 0) { PH_BEGIN; const f32x4* ps = (const f32x4*)(ap->in[1] + (size_t)l * M * PLE); u32x2* pd = (u32x2*)(ws + WS_PB);
; #pragma unroll 1
;               for (int i = gtid; i < M * PLE / 4; i += nthr) { const f32x4 v = __builtin_nontemporal_load(ps + i); u32x2 o; o.x = pk2(v.x, v.y); o.y = pk2(v.z, v.w); pd[i] = o; } }
.LBB0_918:
	s_mov_b32 s12, 0x1fffff
	s_mov_b64 s[24:25], exec
	global_load_dwordx4 v[6:9], v[4:5], off nt
	v_add_u32_e32 v0, s88, v0
	v_cmp_lt_i32_e32 vcc, s12, v0
	v_lshl_add_u64 v[4:5], v[4:5], 0, s[86:87]
	s_or_b64 s[10:11], vcc, s[10:11]
	s_andn2_b64 exec, exec, s[10:11]
	s_mov_b64 s[26:27], exec
	global_load_dwordx4 v[10:13], v[4:5], off nt
	v_add_u32_e32 v0, s88, v0
	v_cmp_lt_i32_e32 vcc, s12, v0
	v_lshl_add_u64 v[4:5], v[4:5], 0, s[86:87]
	s_or_b64 s[10:11], vcc, s[10:11]
	s_andn2_b64 exec, exec, s[10:11]
	s_mov_b64 s[28:29], exec
	global_load_dwordx4 v[14:17], v[4:5], off nt
	v_add_u32_e32 v0, s88, v0
	v_cmp_lt_i32_e32 vcc, s12, v0
	v_lshl_add_u64 v[4:5], v[4:5], 0, s[86:87]
	s_or_b64 s[10:11], vcc, s[10:11]
	s_andn2_b64 exec, exec, s[10:11]
	s_mov_b64 s[30:31], exec
	global_load_dwordx4 v[18:21], v[4:5], off nt
	v_add_u32_e32 v0, s88, v0
	v_cmp_lt_i32_e32 vcc, s12, v0
	v_lshl_add_u64 v[4:5], v[4:5], 0, s[86:87]
	s_or_b64 s[10:11], vcc, s[10:11]
	s_waitcnt vmcnt(0)
	s_mov_b64 exec, s[24:25]
	v_cvt_pk_bf16_f32 v6, v6, v7
	v_cvt_pk_bf16_f32 v7, v8, v9
	global_store_dwordx2 v[2:3], v[6:7], off
	v_lshl_add_u64 v[2:3], v[2:3], 0, s[64:65]
	s_mov_b64 exec, s[26:27]
	v_cvt_pk_bf16_f32 v10, v10, v11
	v_cvt_pk_bf16_f32 v11, v12, v13
	global_store_dwordx2 v[2:3], v[10:11], off
	v_lshl_add_u64 v[2:3], v[2:3], 0, s[64:65]
	s_mov_b64 exec, s[28:29]
	v_cvt_pk_bf16_f32 v14, v14, v15
	v_cvt_pk_bf16_f32 v15, v16, v17
	global_store_dwordx2 v[2:3], v[14:15], off
	v_lshl_add_u64 v[2:3], v[2:3], 0, s[64:65]
	s_mov_b64 exec, s[30:31]
	v_cvt_pk_bf16_f32 v18, v18, v19
	v_cvt_pk_bf16_f32 v19, v20, v21
	global_store_dwordx2 v[2:3], v[18:19], off
	v_lshl_add_u64 v[2:3], v[2:3], 0, s[64:65]
	s_andn2_b64 exec, exec, s[10:11]
	s_cbranch_execnz .LBB0_918
